# conv_act prefetch deepened to two rows ahead (alternating buffers) on top of attention accumulator-move removal and mix0 pointer strength reduction
# speedup vs baseline: 1.0130x; 1.0130x over previous
.LBB0_1112:
	s_or_b64 exec, exec, s[40:41]
	s_movk_i32 s19, 0x1000
	v_add_co_u32_e32 v2, vcc, s19, v68
	v_and_b32_e32 v1, 0xffffefe0, v79
	s_nop 0
	v_addc_co_u32_e32 v3, vcc, 0, v69, vcc
	v_add_co_u32_e32 v122, vcc, 0x2c00, v68
	s_nop 1
	v_addc_co_u32_e32 v123, vcc, 0, v69, vcc
	v_add_co_u32_e32 v124, vcc, 0x2c00, v2
	s_nop 1
	v_addc_co_u32_e32 v125, vcc, 0, v3, vcc
	global_load_dwordx4 v[68:71], v[68:69], off nt
	s_nop 0
	global_load_dwordx4 v[72:75], v[2:3], off offset:1536 nt
	global_load_dwordx4 v[114:117], v[122:123], off nt
	global_load_dwordx4 v[118:121], v[124:125], off offset:1536 nt
	v_add_co_u32_e32 v122, vcc, 0x2c00, v122
	s_nop 1
	v_addc_co_u32_e32 v123, vcc, 0, v123, vcc
	v_add_co_u32_e32 v124, vcc, 0x2c00, v124
	s_nop 1
	v_addc_co_u32_e32 v125, vcc, 0, v125, vcc
	global_load_dwordx4 v[126:129], v[122:123], off nt
	global_load_dwordx4 v[130:133], v[124:125], off offset:1536 nt
	s_movk_i32 s19, 0xe0
	v_mad_i64_i32 v[2:3], s[20:21], v78, s16, 0
	s_waitcnt vmcnt(0)
	v_mov_b32_e32 v79, v6
	v_mov_b32_e32 v6, v10
	v_cmp_eq_u32_e32 vcc, s19, v1
	v_lshlrev_b64 v[76:77], 1, v[76:77]
	s_movk_i32 s19, 0x1600
	v_mov_b32_e32 v80, v14
	v_mov_b32_e32 v14, v18
	v_mov_b32_e32 v81, v22
	v_mov_b32_e32 v22, v26
	v_mov_b32_e32 v82, v30
	v_mov_b32_e32 v30, v34
	v_mov_b32_e32 v83, v38
	v_mov_b32_e32 v38, v42
	v_mov_b32_e32 v94, v46
	v_mov_b32_e32 v46, v50
	v_mov_b32_e32 v95, v54
	v_mov_b32_e32 v54, v58
	v_mov_b32_e32 v96, v62
	v_mov_b32_e32 v62, v66
	v_mov_b32_e32 v10, v9
	v_mov_b32_e32 v9, v6
	v_mov_b32_e32 v6, v5
	v_mov_b32_e32 v5, v79
	v_mad_i64_i32 v[78:79], s[20:21], v78, s19, v[76:77]
	v_lshl_add_u64 v[2:3], v[2:3], 0, v[76:77]
	v_swap_b32 v66, v65
	v_mov_b32_e32 v34, v33
	v_mov_b32_e32 v18, v17
	v_mov_b32_e32 v50, v49
	v_mov_b32_e32 v58, v57
	v_mov_b32_e32 v26, v25
	v_mov_b32_e32 v42, v41
	v_mov_b32_e32 v33, v30
	v_mov_b32_e32 v17, v14
	v_mov_b32_e32 v49, v46
	v_mov_b32_e32 v57, v54
	v_mov_b32_e32 v25, v22
	v_mov_b32_e32 v41, v38
	v_mov_b32_e32 v62, v61
	v_mov_b32_e32 v30, v29
	v_mov_b32_e32 v14, v13
	v_mov_b32_e32 v46, v45
	v_mov_b32_e32 v54, v53
	v_mov_b32_e32 v22, v21
	v_mov_b32_e32 v38, v37
	v_mov_b32_e32 v61, v96
	v_mov_b32_e32 v29, v82
	v_mov_b32_e32 v13, v80
	v_mov_b32_e32 v45, v94
	v_mov_b32_e32 v53, v95
	v_mov_b32_e32 v21, v81
	v_mov_b32_e32 v37, v83
	v_lshl_add_u64 v[94:95], s[52:53], 0, v[78:79]
	v_lshl_add_u64 v[96:97], s[74:75], 0, v[2:3]
	s_mov_b64 s[40:41], 0
	s_xor_b64 s[42:43], vcc, -1
	s_branch .LBB0_1114

.LBB0_1114:
	v_mov_b64_e32 v[78:79], v[70:71]
	v_mov_b64_e32 v[82:83], v[74:75]
	s_cmp_lg_u32 s40, 0x55400
	v_mov_b32_e32 v2, v0
	v_mov_b32_e32 v3, v0
	v_mov_b64_e32 v[76:77], v[68:69]
	v_mov_b64_e32 v[80:81], v[72:73]
	s_cselect_b64 s[20:21], -1, 0
	v_mov_b32_e32 v1, v0
	v_mov_b64_e32 v[70:71], v[2:3]
	v_mov_b64_e32 v[74:75], v[2:3]
	s_or_b64 s[20:21], s[42:43], s[20:21]
	v_mov_b64_e32 v[68:69], v[0:1]
	v_mov_b64_e32 v[72:73], v[0:1]
	s_and_saveexec_b64 s[44:45], s[20:21]
	s_cbranch_execz .LBB0_1113
	s_cmp_lt_u32 s40, 0x52800
	s_cbranch_scc1 .Lcv1110_w4
	s_waitcnt vmcnt(0)
	s_branch .Lcv1110_wd
.Lcv1110_w4:
	s_waitcnt vmcnt(4)
.Lcv1110_wd:
	s_bitcmp1_b32 s40, 10
	s_cbranch_scc1 .Lcv1110_odd
	v_mov_b64_e32 v[68:69], v[114:115]
	v_mov_b64_e32 v[70:71], v[116:117]
	v_mov_b64_e32 v[72:73], v[118:119]
	v_mov_b64_e32 v[74:75], v[120:121]
	s_cmp_lg_u32 s40, 0x4fc00
	s_cselect_b64 vcc, -1, 0
	s_or_b64 vcc, s[42:43], vcc
	s_cmp_lt_u32 s40, 0x52800
	s_cselect_b64 s[20:21], -1, 0
	s_and_b64 vcc, vcc, s[20:21]
	s_and_b64 exec, exec, vcc
	s_cbranch_execz .LBB0_1113
	v_lshl_add_u64 v[2:3], v[96:97], 0, s[40:41]
	v_add_co_u32_e32 v122, vcc, 0x6d57800, v2
	s_nop 1
	v_addc_co_u32_e32 v123, vcc, 0, v3, vcc
	v_add_co_u32_e32 v2, vcc, 0x6d59800, v2
	s_nop 1
	v_addc_co_u32_e32 v3, vcc, 0, v3, vcc
	global_load_dwordx4 v[114:117], v[122:123], off offset:3072 nt
	global_load_dwordx4 v[118:121], v[2:3], off offset:512 nt
	s_branch .LBB0_1113
.Lcv1110_odd:
	v_mov_b64_e32 v[68:69], v[126:127]
	v_mov_b64_e32 v[70:71], v[128:129]
	v_mov_b64_e32 v[72:73], v[130:131]
	v_mov_b64_e32 v[74:75], v[132:133]
	s_cmp_lg_u32 s40, 0x4fc00
	s_cselect_b64 vcc, -1, 0
	s_or_b64 vcc, s[42:43], vcc
	s_cmp_lt_u32 s40, 0x52800
	s_cselect_b64 s[20:21], -1, 0
	s_and_b64 vcc, vcc, s[20:21]
	s_and_b64 exec, exec, vcc
	s_cbranch_execz .LBB0_1113
	v_lshl_add_u64 v[2:3], v[96:97], 0, s[40:41]
	v_add_co_u32_e32 v122, vcc, 0x6d57800, v2
	s_nop 1
	v_addc_co_u32_e32 v123, vcc, 0, v3, vcc
	v_add_co_u32_e32 v2, vcc, 0x6d59800, v2
	s_nop 1
	v_addc_co_u32_e32 v3, vcc, 0, v3, vcc
	global_load_dwordx4 v[126:129], v[122:123], off offset:3072 nt
	global_load_dwordx4 v[130:133], v[2:3], off offset:512 nt
	s_branch .LBB0_1113

.LBB0_1248:
	s_or_b64 exec, exec, s[42:43]
	s_movk_i32 s19, 0x1000
	v_add_co_u32_e32 v2, vcc, s19, v68
	v_and_b32_e32 v1, 0xffffefe0, v79
	s_nop 0
	v_addc_co_u32_e32 v3, vcc, 0, v69, vcc
	v_add_co_u32_e32 v122, vcc, 0x2c00, v68
	s_nop 1
	v_addc_co_u32_e32 v123, vcc, 0, v69, vcc
	v_add_co_u32_e32 v124, vcc, 0x2c00, v2
	s_nop 1
	v_addc_co_u32_e32 v125, vcc, 0, v3, vcc
	global_load_dwordx4 v[68:71], v[68:69], off nt
	s_nop 0
	global_load_dwordx4 v[72:75], v[2:3], off offset:1536 nt
	global_load_dwordx4 v[114:117], v[122:123], off nt
	global_load_dwordx4 v[118:121], v[124:125], off offset:1536 nt
	v_add_co_u32_e32 v122, vcc, 0x2c00, v122
	s_nop 1
	v_addc_co_u32_e32 v123, vcc, 0, v123, vcc
	v_add_co_u32_e32 v124, vcc, 0x2c00, v124
	s_nop 1
	v_addc_co_u32_e32 v125, vcc, 0, v125, vcc
	global_load_dwordx4 v[126:129], v[122:123], off nt
	global_load_dwordx4 v[130:133], v[124:125], off offset:1536 nt
	s_movk_i32 s19, 0xe0
	v_mad_i64_i32 v[2:3], s[20:21], v78, s16, 0
	s_waitcnt vmcnt(0)
	v_mov_b32_e32 v79, v6
	v_mov_b32_e32 v6, v10
	v_cmp_eq_u32_e32 vcc, s19, v1
	v_lshlrev_b64 v[76:77], 1, v[76:77]
	s_movk_i32 s19, 0x1600
	v_mov_b32_e32 v80, v14
	v_mov_b32_e32 v14, v18
	v_mov_b32_e32 v81, v22
	v_mov_b32_e32 v22, v26
	v_mov_b32_e32 v82, v30
	v_mov_b32_e32 v30, v34
	v_mov_b32_e32 v83, v38
	v_mov_b32_e32 v38, v42
	v_mov_b32_e32 v94, v46
	v_mov_b32_e32 v46, v50
	v_mov_b32_e32 v95, v54
	v_mov_b32_e32 v54, v58
	v_mov_b32_e32 v96, v62
	v_mov_b32_e32 v62, v66
	v_mov_b32_e32 v10, v9
	v_mov_b32_e32 v9, v6
	v_mov_b32_e32 v6, v5
	v_mov_b32_e32 v5, v79
	v_mad_i64_i32 v[78:79], s[20:21], v78, s19, v[76:77]
	v_lshl_add_u64 v[2:3], v[2:3], 0, v[76:77]
	v_swap_b32 v66, v65
	v_mov_b32_e32 v34, v33
	v_mov_b32_e32 v18, v17
	v_mov_b32_e32 v50, v49
	v_mov_b32_e32 v58, v57
	v_mov_b32_e32 v26, v25
	v_mov_b32_e32 v42, v41
	v_mov_b32_e32 v33, v30
	v_mov_b32_e32 v17, v14
	v_mov_b32_e32 v49, v46
	v_mov_b32_e32 v57, v54
	v_mov_b32_e32 v25, v22
	v_mov_b32_e32 v41, v38
	v_mov_b32_e32 v62, v61
	v_mov_b32_e32 v30, v29
	v_mov_b32_e32 v14, v13
	v_mov_b32_e32 v46, v45
	v_mov_b32_e32 v54, v53
	v_mov_b32_e32 v22, v21
	v_mov_b32_e32 v38, v37
	v_mov_b32_e32 v61, v96
	v_mov_b32_e32 v29, v82
	v_mov_b32_e32 v13, v80
	v_mov_b32_e32 v45, v94
	v_mov_b32_e32 v53, v95
	v_mov_b32_e32 v21, v81
	v_mov_b32_e32 v37, v83
	v_lshl_add_u64 v[94:95], s[38:39], 0, v[78:79]
	v_lshl_add_u64 v[96:97], s[74:75], 0, v[2:3]
	s_mov_b64 s[42:43], 0
	s_xor_b64 s[44:45], vcc, -1
	s_branch .LBB0_1250

.LBB0_1250:
	v_mov_b64_e32 v[78:79], v[70:71]
	v_mov_b64_e32 v[82:83], v[74:75]
	s_cmp_lg_u32 s42, 0x55400
	v_mov_b32_e32 v2, v0
	v_mov_b32_e32 v3, v0
	v_mov_b64_e32 v[76:77], v[68:69]
	v_mov_b64_e32 v[80:81], v[72:73]
	s_cselect_b64 s[20:21], -1, 0
	v_mov_b32_e32 v1, v0
	v_mov_b64_e32 v[70:71], v[2:3]
	v_mov_b64_e32 v[74:75], v[2:3]
	s_or_b64 s[20:21], s[44:45], s[20:21]
	v_mov_b64_e32 v[68:69], v[0:1]
	v_mov_b64_e32 v[72:73], v[0:1]
	s_and_saveexec_b64 s[46:47], s[20:21]
	s_cbranch_execz .LBB0_1249
	s_cmp_lt_u32 s42, 0x52800
	s_cbranch_scc1 .Lcv1246_w4
	s_waitcnt vmcnt(0)
	s_branch .Lcv1246_wd

.Lcv1246_wd:
	s_bitcmp1_b32 s42, 10
	s_cbranch_scc1 .Lcv1246_odd
	v_mov_b64_e32 v[68:69], v[114:115]
	v_mov_b64_e32 v[70:71], v[116:117]
	v_mov_b64_e32 v[72:73], v[118:119]
	v_mov_b64_e32 v[74:75], v[120:121]
	s_cmp_lg_u32 s42, 0x4fc00
	s_cselect_b64 vcc, -1, 0
	s_or_b64 vcc, s[44:45], vcc
	s_cmp_lt_u32 s42, 0x52800
	s_cselect_b64 s[20:21], -1, 0
	s_and_b64 vcc, vcc, s[20:21]
	s_and_b64 exec, exec, vcc
	s_cbranch_execz .LBB0_1249
	v_lshl_add_u64 v[2:3], v[96:97], 0, s[42:43]
	v_add_co_u32_e32 v122, vcc, 0x6d57800, v2
	s_nop 1
	v_addc_co_u32_e32 v123, vcc, 0, v3, vcc
	v_add_co_u32_e32 v2, vcc, 0x6d59800, v2
	s_nop 1
	v_addc_co_u32_e32 v3, vcc, 0, v3, vcc
	global_load_dwordx4 v[114:117], v[122:123], off offset:3072 nt
	global_load_dwordx4 v[118:121], v[2:3], off offset:512 nt
	s_branch .LBB0_1249
.Lcv1246_odd:
	v_mov_b64_e32 v[68:69], v[126:127]
	v_mov_b64_e32 v[70:71], v[128:129]
	v_mov_b64_e32 v[72:73], v[130:131]
	v_mov_b64_e32 v[74:75], v[132:133]
	s_cmp_lg_u32 s42, 0x4fc00
	s_cselect_b64 vcc, -1, 0
	s_or_b64 vcc, s[44:45], vcc
	s_cmp_lt_u32 s42, 0x52800
	s_cselect_b64 s[20:21], -1, 0
	s_and_b64 vcc, vcc, s[20:21]
	s_and_b64 exec, exec, vcc
	s_cbranch_execz .LBB0_1249
	v_lshl_add_u64 v[2:3], v[96:97], 0, s[42:43]
	v_add_co_u32_e32 v122, vcc, 0x6d57800, v2
	s_nop 1
	v_addc_co_u32_e32 v123, vcc, 0, v3, vcc
	v_add_co_u32_e32 v2, vcc, 0x6d59800, v2
	s_nop 1
	v_addc_co_u32_e32 v3, vcc, 0, v3, vcc
	global_load_dwordx4 v[126:129], v[122:123], off offset:3072 nt
	global_load_dwordx4 v[130:133], v[2:3], off offset:512 nt
	s_branch .LBB0_1249

.LBB0_2357:
	s_or_b64 exec, exec, s[36:37]
	v_add_co_u32_e32 v2, vcc, s30, v68
	v_and_b32_e32 v1, 0xffffefe0, v79
	s_nop 0
	v_addc_co_u32_e32 v3, vcc, 0, v69, vcc
	v_add_co_u32_e32 v122, vcc, 0x2c00, v68
	s_nop 1
	v_addc_co_u32_e32 v123, vcc, 0, v69, vcc
	v_add_co_u32_e32 v124, vcc, 0x2c00, v2
	s_nop 1
	v_addc_co_u32_e32 v125, vcc, 0, v3, vcc
	global_load_dwordx4 v[68:71], v[68:69], off nt
	s_nop 0
	global_load_dwordx4 v[72:75], v[2:3], off offset:1536 nt
	global_load_dwordx4 v[114:117], v[122:123], off nt
	global_load_dwordx4 v[118:121], v[124:125], off offset:1536 nt
	v_add_co_u32_e32 v122, vcc, 0x2c00, v122
	s_nop 1
	v_addc_co_u32_e32 v123, vcc, 0, v123, vcc
	v_add_co_u32_e32 v124, vcc, 0x2c00, v124
	s_nop 1
	v_addc_co_u32_e32 v125, vcc, 0, v125, vcc
	global_load_dwordx4 v[126:129], v[122:123], off nt
	global_load_dwordx4 v[130:133], v[124:125], off offset:1536 nt
	v_mad_i64_i32 v[2:3], s[36:37], v78, s26, 0
	s_waitcnt vmcnt(0)
	v_mov_b32_e32 v79, v6
	v_mov_b32_e32 v6, v10
	v_lshlrev_b64 v[76:77], 1, v[76:77]
	v_mov_b32_e32 v80, v14
	v_mov_b32_e32 v14, v18
	v_mov_b32_e32 v81, v22
	v_mov_b32_e32 v22, v26
	v_mov_b32_e32 v82, v30
	v_mov_b32_e32 v30, v34
	v_mov_b32_e32 v83, v38
	v_mov_b32_e32 v38, v42
	v_mov_b32_e32 v94, v46
	v_mov_b32_e32 v46, v50
	v_mov_b32_e32 v95, v54
	v_mov_b32_e32 v54, v58
	v_mov_b32_e32 v96, v62
	v_mov_b32_e32 v62, v66
	v_cmp_eq_u32_e32 vcc, s27, v1
	v_mov_b32_e32 v10, v9
	v_mov_b32_e32 v9, v6
	v_mov_b32_e32 v6, v5
	v_mov_b32_e32 v5, v79
	v_mad_i64_i32 v[78:79], s[36:37], v78, s31, v[76:77]
	v_lshl_add_u64 v[2:3], v[2:3], 0, v[76:77]
	v_swap_b32 v66, v65
	v_mov_b32_e32 v34, v33
	v_mov_b32_e32 v18, v17
	v_mov_b32_e32 v50, v49
	v_swap_b32 v58, v57
	v_mov_b32_e32 v26, v25
	v_mov_b32_e32 v42, v41
	v_mov_b32_e32 v33, v30
	v_mov_b32_e32 v17, v14
	v_mov_b32_e32 v49, v46
	v_mov_b32_e32 v25, v22
	v_mov_b32_e32 v41, v38
	v_mov_b32_e32 v62, v61
	v_mov_b32_e32 v30, v29
	v_mov_b32_e32 v14, v13
	v_mov_b32_e32 v46, v45
	v_mov_b32_e32 v54, v53
	v_mov_b32_e32 v22, v21
	v_mov_b32_e32 v38, v37
	v_mov_b32_e32 v61, v96
	v_mov_b32_e32 v29, v82
	v_mov_b32_e32 v13, v80
	v_mov_b32_e32 v45, v94
	v_mov_b32_e32 v53, v95
	v_mov_b32_e32 v21, v81
	v_mov_b32_e32 v37, v83
	v_lshl_add_u64 v[94:95], s[52:53], 0, v[78:79]
	v_lshl_add_u64 v[96:97], s[74:75], 0, v[2:3]
	s_mov_b64 s[36:37], 0
	s_xor_b64 s[38:39], vcc, -1
	s_branch .LBB0_2359

.LBB0_2359:
	v_mov_b64_e32 v[78:79], v[70:71]
	v_mov_b64_e32 v[82:83], v[74:75]
	s_cmp_lg_u32 s36, 0x55400
	v_mov_b32_e32 v2, v0
	v_mov_b32_e32 v3, v0
	v_mov_b64_e32 v[76:77], v[68:69]
	v_mov_b64_e32 v[80:81], v[72:73]
	s_cselect_b64 s[40:41], -1, 0
	v_mov_b32_e32 v1, v0
	v_mov_b64_e32 v[70:71], v[2:3]
	v_mov_b64_e32 v[74:75], v[2:3]
	s_or_b64 s[44:45], s[38:39], s[40:41]
	v_mov_b64_e32 v[68:69], v[0:1]
	v_mov_b64_e32 v[72:73], v[0:1]
	s_and_saveexec_b64 s[40:41], s[44:45]
	s_cbranch_execz .LBB0_2358
	s_cmp_lt_u32 s36, 0x52800
	s_cbranch_scc1 .Lcv2355_w4
	s_waitcnt vmcnt(0)
	s_branch .Lcv2355_wd

.Lcv2355_wd:
	s_bitcmp1_b32 s36, 10
	s_cbranch_scc1 .Lcv2355_odd
	v_mov_b64_e32 v[68:69], v[114:115]
	v_mov_b64_e32 v[70:71], v[116:117]
	v_mov_b64_e32 v[72:73], v[118:119]
	v_mov_b64_e32 v[74:75], v[120:121]
	s_cmp_lg_u32 s36, 0x4fc00
	s_cselect_b64 vcc, -1, 0
	s_or_b64 vcc, s[38:39], vcc
	s_cmp_lt_u32 s36, 0x52800
	s_cselect_b64 s[44:45], -1, 0
	s_and_b64 vcc, vcc, s[44:45]
	s_and_b64 exec, exec, vcc
	s_cbranch_execz .LBB0_2358
	v_lshl_add_u64 v[2:3], v[96:97], 0, s[36:37]
	v_add_co_u32_e32 v122, vcc, 0x6d57800, v2
	s_nop 1
	v_addc_co_u32_e32 v123, vcc, 0, v3, vcc
	v_add_co_u32_e32 v2, vcc, 0x6d59800, v2
	s_nop 1
	v_addc_co_u32_e32 v3, vcc, 0, v3, vcc
	global_load_dwordx4 v[114:117], v[122:123], off offset:3072 nt
	global_load_dwordx4 v[118:121], v[2:3], off offset:512 nt
	s_branch .LBB0_2358
.Lcv2355_odd:
	v_mov_b64_e32 v[68:69], v[126:127]
	v_mov_b64_e32 v[70:71], v[128:129]
	v_mov_b64_e32 v[72:73], v[130:131]
	v_mov_b64_e32 v[74:75], v[132:133]
	s_cmp_lg_u32 s36, 0x4fc00
	s_cselect_b64 vcc, -1, 0
	s_or_b64 vcc, s[38:39], vcc
	s_cmp_lt_u32 s36, 0x52800
	s_cselect_b64 s[44:45], -1, 0
	s_and_b64 vcc, vcc, s[44:45]
	s_and_b64 exec, exec, vcc
	s_cbranch_execz .LBB0_2358
	v_lshl_add_u64 v[2:3], v[96:97], 0, s[36:37]
	v_add_co_u32_e32 v122, vcc, 0x6d57800, v2
	s_nop 1
	v_addc_co_u32_e32 v123, vcc, 0, v3, vcc
	v_add_co_u32_e32 v2, vcc, 0x6d59800, v2
	s_nop 1
	v_addc_co_u32_e32 v3, vcc, 0, v3, vcc
	global_load_dwordx4 v[126:129], v[122:123], off offset:3072 nt
	global_load_dwordx4 v[130:133], v[2:3], off offset:512 nt
	s_branch .LBB0_2358

.LBB0_2493:
	s_or_b64 exec, exec, s[34:35]
	v_add_co_u32_e32 v2, vcc, s41, v68
	v_and_b32_e32 v1, 0xffffefe0, v79
	s_nop 0
	v_addc_co_u32_e32 v3, vcc, 0, v69, vcc
	v_add_co_u32_e32 v122, vcc, 0x2c00, v68
	s_nop 1
	v_addc_co_u32_e32 v123, vcc, 0, v69, vcc
	v_add_co_u32_e32 v124, vcc, 0x2c00, v2
	s_nop 1
	v_addc_co_u32_e32 v125, vcc, 0, v3, vcc
	global_load_dwordx4 v[68:71], v[68:69], off nt
	s_nop 0
	global_load_dwordx4 v[72:75], v[2:3], off offset:1536 nt
	global_load_dwordx4 v[114:117], v[122:123], off nt
	global_load_dwordx4 v[118:121], v[124:125], off offset:1536 nt
	v_add_co_u32_e32 v122, vcc, 0x2c00, v122
	s_nop 1
	v_addc_co_u32_e32 v123, vcc, 0, v123, vcc
	v_add_co_u32_e32 v124, vcc, 0x2c00, v124
	s_nop 1
	v_addc_co_u32_e32 v125, vcc, 0, v125, vcc
	global_load_dwordx4 v[126:129], v[122:123], off nt
	global_load_dwordx4 v[130:133], v[124:125], off offset:1536 nt
	v_mad_i64_i32 v[2:3], s[34:35], v78, s33, 0
	s_waitcnt vmcnt(0)
	v_mov_b32_e32 v79, v6
	v_mov_b32_e32 v6, v10
	v_lshlrev_b64 v[76:77], 1, v[76:77]
	v_mov_b32_e32 v80, v14
	v_mov_b32_e32 v14, v18
	v_mov_b32_e32 v81, v22
	v_mov_b32_e32 v22, v26
	v_mov_b32_e32 v82, v30
	v_mov_b32_e32 v30, v34
	v_mov_b32_e32 v83, v38
	v_mov_b32_e32 v38, v42
	v_mov_b32_e32 v94, v46
	v_mov_b32_e32 v46, v50
	v_mov_b32_e32 v95, v54
	v_mov_b32_e32 v54, v58
	v_mov_b32_e32 v96, v62
	v_mov_b32_e32 v62, v66
	v_cmp_eq_u32_e32 vcc, s40, v1
	v_mov_b32_e32 v10, v9
	v_mov_b32_e32 v9, v6
	v_mov_b32_e32 v6, v5
	v_mov_b32_e32 v5, v79
	v_mad_i64_i32 v[78:79], s[34:35], v78, s42, v[76:77]
	v_lshl_add_u64 v[2:3], v[2:3], 0, v[76:77]
	v_swap_b32 v66, v65
	v_mov_b32_e32 v34, v33
	v_mov_b32_e32 v18, v17
	v_mov_b32_e32 v50, v49
	v_swap_b32 v58, v57
	v_mov_b32_e32 v26, v25
	v_mov_b32_e32 v42, v41
	v_mov_b32_e32 v33, v30
	v_mov_b32_e32 v17, v14
	v_mov_b32_e32 v49, v46
	v_mov_b32_e32 v25, v22
	v_mov_b32_e32 v41, v38
	v_mov_b32_e32 v62, v61
	v_mov_b32_e32 v30, v29
	v_mov_b32_e32 v14, v13
	v_mov_b32_e32 v46, v45
	v_mov_b32_e32 v54, v53
	v_mov_b32_e32 v22, v21
	v_mov_b32_e32 v38, v37
	v_mov_b32_e32 v61, v96
	v_mov_b32_e32 v29, v82
	v_mov_b32_e32 v13, v80
	v_mov_b32_e32 v45, v94
	v_mov_b32_e32 v53, v95
	v_mov_b32_e32 v21, v81
	v_mov_b32_e32 v37, v83
	v_lshl_add_u64 v[94:95], s[24:25], 0, v[78:79]
	v_lshl_add_u64 v[96:97], s[74:75], 0, v[2:3]
	s_mov_b64 s[34:35], 0
	s_xor_b64 s[36:37], vcc, -1
	s_branch .LBB0_2495

.LBB0_2495:
	v_mov_b64_e32 v[78:79], v[70:71]
	v_mov_b64_e32 v[82:83], v[74:75]
	s_cmp_lg_u32 s34, 0x55400
	v_mov_b32_e32 v2, v0
	v_mov_b32_e32 v3, v0
	v_mov_b64_e32 v[76:77], v[68:69]
	v_mov_b64_e32 v[80:81], v[72:73]
	s_cselect_b64 s[38:39], -1, 0
	v_mov_b32_e32 v1, v0
	v_mov_b64_e32 v[70:71], v[2:3]
	v_mov_b64_e32 v[74:75], v[2:3]
	s_or_b64 s[46:47], s[36:37], s[38:39]
	v_mov_b64_e32 v[68:69], v[0:1]
	v_mov_b64_e32 v[72:73], v[0:1]
	s_and_saveexec_b64 s[38:39], s[46:47]
	s_cbranch_execz .LBB0_2494
	s_cmp_lt_u32 s34, 0x52800
	s_cbranch_scc1 .Lcv2491_w4
	s_waitcnt vmcnt(0)
	s_branch .Lcv2491_wd

.Lcv2491_wd:
	s_bitcmp1_b32 s34, 10
	s_cbranch_scc1 .Lcv2491_odd
	v_mov_b64_e32 v[68:69], v[114:115]
	v_mov_b64_e32 v[70:71], v[116:117]
	v_mov_b64_e32 v[72:73], v[118:119]
	v_mov_b64_e32 v[74:75], v[120:121]
	s_cmp_lg_u32 s34, 0x4fc00
	s_cselect_b64 vcc, -1, 0
	s_or_b64 vcc, s[36:37], vcc
	s_cmp_lt_u32 s34, 0x52800
	s_cselect_b64 s[46:47], -1, 0
	s_and_b64 vcc, vcc, s[46:47]
	s_and_b64 exec, exec, vcc
	s_cbranch_execz .LBB0_2494
	v_lshl_add_u64 v[2:3], v[96:97], 0, s[34:35]
	v_add_co_u32_e32 v122, vcc, 0x6d57800, v2
	s_nop 1
	v_addc_co_u32_e32 v123, vcc, 0, v3, vcc
	v_add_co_u32_e32 v2, vcc, 0x6d59800, v2
	s_nop 1
	v_addc_co_u32_e32 v3, vcc, 0, v3, vcc
	global_load_dwordx4 v[114:117], v[122:123], off offset:3072 nt
	global_load_dwordx4 v[118:121], v[2:3], off offset:512 nt
	s_branch .LBB0_2494
.Lcv2491_odd:
	v_mov_b64_e32 v[68:69], v[126:127]
	v_mov_b64_e32 v[70:71], v[128:129]
	v_mov_b64_e32 v[72:73], v[130:131]
	v_mov_b64_e32 v[74:75], v[132:133]
	s_cmp_lg_u32 s34, 0x4fc00
	s_cselect_b64 vcc, -1, 0
	s_or_b64 vcc, s[36:37], vcc
	s_cmp_lt_u32 s34, 0x52800
	s_cselect_b64 s[46:47], -1, 0
	s_and_b64 vcc, vcc, s[46:47]
	s_and_b64 exec, exec, vcc
	s_cbranch_execz .LBB0_2494
	v_lshl_add_u64 v[2:3], v[96:97], 0, s[34:35]
	v_add_co_u32_e32 v122, vcc, 0x6d57800, v2
	s_nop 1
	v_addc_co_u32_e32 v123, vcc, 0, v3, vcc
	v_add_co_u32_e32 v2, vcc, 0x6d59800, v2
	s_nop 1
	v_addc_co_u32_e32 v3, vcc, 0, v3, vcc
	global_load_dwordx4 v[126:129], v[122:123], off offset:3072 nt
	global_load_dwordx4 v[130:133], v[2:3], off offset:512 nt
	s_branch .LBB0_2494
